# EpiPg epilogue de-serialisation: column-half-1 loads issued with their column-half-0 siblings (same address + 256 B) into spare registers; batches 2 and 4 copy instead of loading
# speedup vs baseline: 1.0124x; 1.0033x over previous
; __device__ __forceinline__ float sigmoid_f(float x) { return __builtin_amdgcn_rcpf(1.0f + __builtin_amdgcn_exp2f(-x * 1.4426950408889634f)); }
;     __device__ __forceinline__ void operator()(const f32x4 (&acc)[2][2][4][2], const Unit& u, int wr, int wc, int fr, int fq) const {
;     ...
; #pragma unroll
;         for (int ai = 0; ai < 2; ++ai) {
;             float s[4] = {0.f, 0.f, 0.f, 0.f};
; #pragma unroll
;             for (int bj = 0; bj < 2; ++bj) { const int col = u.pn * BM + bj * HALF + wc * 32 + fq * 8;
;                 u32x4 hw[4], pw[4];
; #pragma unroll
;                 for (int m = 0; m < 4; ++m) { const size_t off = (size_t)(row0 + ai * HALF + m * 16) * DM + col; hw[m] = *(const u32x4*)(HBi + off); pw[m] = *(const u32x4*)(P + off); }
;                 asm volatile("" ::: "memory");
; #pragma unroll
;                 for (int m = 0; m < 4; ++m) { const size_t off = (size_t)(row0 + ai * HALF + m * 16) * DM + col; float v[8];
; #pragma unroll
;                     for (int e = 0; e < 4; ++e) {
;                         const unsigned w = pw[m][e]; const float p0 = __uint_as_float(w << 16), p1 = __uint_as_float(w & 0xffff0000u);
;                         const unsigned g = hw[m][e]; const float b0 = __uint_as_float(g << 16), b1 = __uint_as_float(g & 0xffff0000u);
;                         const float a0 = (e < 2) ? acc[ai][bj][m][0][2 * e] : acc[ai][bj][m][1][2 * e - 4], a1 = (e < 2) ? acc[ai][bj][m][0][2 * e + 1] : acc[ai][bj][m][1][2 * e - 3];
;                         v[2 * e] = b0 + p0 * sigmoid_f(a0); v[2 * e + 1] = b1 + p1 * sigmoid_f(a1); }
.LBB0_1345:
	s_getreg_b32 s4, hwreg(HW_REG_HW_ID, 0, 6)
	s_lshl_b32 s4, s4, 2
	s_and_b32 s4, s4, 0xfc
	s_add_i32 s4, s4, 0x20040
	v_mov_b32_e32 v130, s4
	ds_read_b32 v130, v130
	v_mov_b32_e32 v131, v1
	s_lshl_b32 s5, s33, 8
	v_mbcnt_lo_u32_b32 v131, -1, v131
	v_mbcnt_hi_u32_b32 v131, -1, v131
	s_waitcnt lgkmcnt(0)
	v_readfirstlane_b32 s4, v130
	v_bfe_u32 v196, v131, 4, 2
	v_mul_f32_e32 v122, 0xbfb8aa3b, v122
	v_lshl_or_b32 v130, s4, 6, v131
	v_mul_f32_e32 v123, 0xbfb8aa3b, v123
	v_readfirstlane_b32 s4, v130
	s_bfe_u32 s15, s4, 0x20006
	s_ashr_i32 s4, s4, 2
	s_andn2_b32 s4, s4, 63
	s_add_i32 s4, s4, s5
	v_lshlrev_b32_e32 v130, 3, v196
	v_and_or_b32 v150, v131, 15, s4
	v_lshl_or_b32 v130, s15, 5, v130
	v_lshl_or_b32 v148, s51, 8, v130
	v_ashrrev_i32_e32 v151, 31, v150
	v_ashrrev_i32_e32 v149, 31, v148
	v_lshlrev_b64 v[158:159], 11, v[150:151]
	v_lshl_add_u64 v[130:131], v[158:159], 0, v[148:149]
	v_lshlrev_b64 v[130:131], 1, v[130:131]
	v_lshl_add_u64 v[132:133], s[10:11], 0, v[130:131]
	v_lshl_add_u64 v[130:131], s[0:1], 0, v[130:131]
	global_load_dwordx4 v[216:219], v[132:133], off offset:256
	global_load_dwordx4 v[160:163], v[132:133], off
	global_load_dwordx4 v[220:223], v[130:131], off offset:256
	global_load_dwordx4 v[164:167], v[130:131], off
	v_or_b32_e32 v154, 16, v150
	v_ashrrev_i32_e32 v155, 31, v154
	v_lshlrev_b64 v[176:177], 11, v[154:155]
	v_mul_f32_e32 v130, 0xbfb8aa3b, v126
	v_mul_f32_e32 v131, 0xbfb8aa3b, v127
	v_lshl_add_u64 v[126:127], v[176:177], 0, v[148:149]
	v_lshlrev_b64 v[126:127], 1, v[126:127]
	v_mul_f32_e32 v132, 0xbfb8aa3b, v128
	v_mul_f32_e32 v133, 0xbfb8aa3b, v129
	v_lshl_add_u64 v[128:129], s[0:1], 0, v[126:127]
	v_lshl_add_u64 v[126:127], s[10:11], 0, v[126:127]
	global_load_dwordx4 v[224:227], v[128:129], off offset:256
	global_load_dwordx4 v[168:171], v[128:129], off
	global_load_dwordx4 v[228:231], v[126:127], off offset:256
	global_load_dwordx4 v[172:175], v[126:127], off
	v_exp_f32_e32 v126, v130
	v_exp_f32_e32 v127, v131
	v_exp_f32_e32 v122, v122
	v_exp_f32_e32 v123, v123
	v_exp_f32_e32 v128, v132
	v_exp_f32_e32 v129, v133
	v_or_b32_e32 v156, 32, v150
	v_or_b32_e32 v152, 48, v150
	v_ashrrev_i32_e32 v157, 31, v156
	v_ashrrev_i32_e32 v153, 31, v152
	v_add_f32_e32 v126, 1.0, v126
	v_add_f32_e32 v127, 1.0, v127
	v_add_f32_e32 v122, 1.0, v122
	v_add_f32_e32 v123, 1.0, v123
	v_lshlrev_b64 v[180:181], 11, v[156:157]
	v_lshlrev_b64 v[178:179], 11, v[152:153]
	v_rcp_f32_e32 v184, v126
	v_rcp_f32_e32 v185, v127
	v_rcp_f32_e32 v188, v122
	v_rcp_f32_e32 v189, v123
	v_lshl_add_u64 v[122:123], v[180:181], 0, v[148:149]
	v_lshl_add_u64 v[126:127], v[178:179], 0, v[148:149]
	v_add_f32_e32 v128, 1.0, v128
	v_add_f32_e32 v129, 1.0, v129
	v_lshlrev_b64 v[122:123], 1, v[122:123]
	v_lshlrev_b64 v[126:127], 1, v[126:127]
	v_rcp_f32_e32 v186, v128
	v_rcp_f32_e32 v187, v129
	v_lshl_add_u64 v[128:129], s[0:1], 0, v[122:123]
	v_lshl_add_u64 v[130:131], s[0:1], 0, v[126:127]
	v_lshl_add_u64 v[132:133], s[10:11], 0, v[126:127]
	v_lshl_add_u64 v[122:123], s[10:11], 0, v[122:123]
	global_load_dwordx4 v[232:235], v[128:129], off offset:256
	global_load_dwordx4 v[134:137], v[128:129], off
	global_load_dwordx4 v[236:239], v[122:123], off offset:256
	global_load_dwordx4 v[206:209], v[122:123], off
	s_nop 0
	global_load_dwordx4 v[240:243], v[130:131], off offset:256
	global_load_dwordx4 v[126:129], v[130:131], off
	s_nop 0
	global_load_dwordx4 v[244:247], v[132:133], off offset:256
	global_load_dwordx4 v[130:133], v[132:133], off
	v_mul_f32_e32 v124, 0xbfb8aa3b, v124
	v_mul_f32_e32 v119, 0xbfb8aa3b, v119
	v_exp_f32_e32 v119, v119
	v_mul_f32_e32 v118, 0xbfb8aa3b, v118
	v_exp_f32_e32 v118, v118
	v_add_f32_e32 v119, 1.0, v119
	v_rcp_f32_e32 v119, v119
	v_mul_f32_e32 v115, 0xbfb8aa3b, v115
	v_exp_f32_e32 v115, v115
	v_add_f32_e32 v118, 1.0, v118
	v_rcp_f32_e32 v118, v118
	v_mul_f32_e32 v114, 0xbfb8aa3b, v114
	v_add_f32_e32 v115, 1.0, v115
	v_rcp_f32_e32 v115, v115
	v_exp_f32_e32 v114, v114
	v_mul_f32_e32 v111, 0xbfb8aa3b, v111
	v_exp_f32_e32 v111, v111
	v_mul_f32_e32 v110, 0xbfb8aa3b, v110
	v_add_f32_e32 v114, 1.0, v114
	v_rcp_f32_e32 v114, v114
	v_add_f32_e32 v111, 1.0, v111
	v_rcp_f32_e32 v111, v111
	v_exp_f32_e32 v110, v110
	v_mul_f32_e32 v107, 0xbfb8aa3b, v107
	v_exp_f32_e32 v107, v107
	v_mul_f32_e32 v106, 0xbfb8aa3b, v106
	v_add_f32_e32 v110, 1.0, v110
	v_rcp_f32_e32 v110, v110
	v_add_f32_e32 v107, 1.0, v107
	v_rcp_f32_e32 v107, v107
	v_exp_f32_e32 v106, v106
	v_mul_f32_e32 v103, 0xbfb8aa3b, v103
	s_waitcnt vmcnt(0)
; __device__ __forceinline__ float sigmoid_f(float x) { return __builtin_amdgcn_rcpf(1.0f + __builtin_amdgcn_exp2f(-x * 1.4426950408889634f)); }
;     __device__ __forceinline__ void operator()(const f32x4 (&acc)[2][2][4][2], const Unit& u, int wr, int wc, int fr, int fq) const {
;     ...
;                 for (int m = 0; m < 4; ++m) { const size_t off = (size_t)(row0 + ai * HALF + m * 16) * DM + col; hw[m] = *(const u32x4*)(HBi + off); pw[m] = *(const u32x4*)(P + off); }
;                 asm volatile("" ::: "memory");
; #pragma unroll
;                 for (int m = 0; m < 4; ++m) { const size_t off = (size_t)(row0 + ai * HALF + m * 16) * DM + col; float v[8];
; #pragma unroll
;                     for (int e = 0; e < 4; ++e) {
;                         const unsigned w = pw[m][e]; const float p0 = __uint_as_float(w << 16), p1 = __uint_as_float(w & 0xffff0000u);
;                         const unsigned g = hw[m][e]; const float b0 = __uint_as_float(g << 16), b1 = __uint_as_float(g & 0xffff0000u);
;                         const float a0 = (e < 2) ? acc[ai][bj][m][0][2 * e] : acc[ai][bj][m][1][2 * e - 4], a1 = (e < 2) ? acc[ai][bj][m][0][2 * e + 1] : acc[ai][bj][m][1][2 * e - 3];
;                         v[2 * e] = b0 + p0 * sigmoid_f(a0); v[2 * e + 1] = b1 + p1 * sigmoid_f(a1); }
; #pragma unroll
;                     for (int e = 0; e < 8; ++e) s[m] += v[e] * v[e];
;                     store8(HBo + off, v); }
	v_and_b32_e32 v123, 0xffff0000, v160
	v_and_b32_e32 v198, 0xffff0000, v164
	v_lshlrev_b32_e32 v122, 16, v160
	v_lshlrev_b32_e32 v197, 16, v164
	v_fmac_f32_e32 v198, v185, v123
	v_mul_f32_e32 v123, 0xbfb8aa3b, v125
	v_fmac_f32_e32 v197, v184, v122
	v_exp_f32_e32 v122, v124
	v_exp_f32_e32 v123, v123
	v_lshlrev_b32_e32 v199, 16, v165
	v_and_b32_e32 v200, 0xffff0000, v165
	v_add_f32_e32 v122, 1.0, v122
	v_add_f32_e32 v123, 1.0, v123
	v_rcp_f32_e32 v122, v122
	v_rcp_f32_e32 v123, v123
	v_lshlrev_b32_e32 v165, 16, v163
	v_and_b32_e32 v124, 0xffff0000, v163
	v_lshlrev_b32_e32 v210, 16, v167
	v_and_b32_e32 v167, 0xffff0000, v167
	v_fmac_f32_e32 v210, v122, v165
	v_fmac_f32_e32 v167, v123, v124
	v_lshlrev_b64 v[122:123], 12, v[150:151]
	v_lshlrev_b32_e32 v160, 16, v161
	v_and_b32_e32 v161, 0xffff0000, v161
	v_lshl_add_u64 v[124:125], s[8:9], 0, v[122:123]
	v_lshlrev_b64 v[122:123], 1, v[148:149]
	v_lshlrev_b32_e32 v164, 16, v162
	v_and_b32_e32 v162, 0xffff0000, v162
	v_lshlrev_b32_e32 v201, 16, v166
	v_and_b32_e32 v166, 0xffff0000, v166
	v_fmac_f32_e32 v199, v186, v160
	v_fmac_f32_e32 v200, v187, v161
	v_lshl_add_u64 v[124:125], v[124:125], 0, v[122:123]
	v_cvt_pk_bf16_f32 v160, v197, v198
	v_cvt_pk_bf16_f32 v161, v199, v200
	v_fmac_f32_e32 v201, v188, v164
	v_fmac_f32_e32 v166, v189, v162
	v_cvt_pk_bf16_f32 v162, v201, v166
	v_cvt_pk_bf16_f32 v163, v210, v167
	global_store_dwordx4 v[124:125], v[160:163], off
	v_and_b32_e32 v185, 0xffff0000, v168
	v_lshlrev_b32_e32 v184, 16, v168
	v_and_b32_e32 v161, 0xffff0000, v172
	v_fmac_f32_e32 v185, v119, v161
	v_mul_f32_e32 v119, 0xbfb8aa3b, v120
	v_exp_f32_e32 v119, v119
	v_lshlrev_b32_e32 v160, 16, v172
	v_fmac_f32_e32 v184, v118, v160
	v_lshlrev_b32_e32 v118, 16, v173
	v_add_f32_e32 v119, 1.0, v119
	v_rcp_f32_e32 v119, v119
	v_lshlrev_b32_e32 v187, 16, v169
	v_and_b32_e32 v188, 0xffff0000, v170
	v_lshlrev_b32_e32 v189, 16, v170
	v_fmac_f32_e32 v187, v119, v118
	v_and_b32_e32 v119, 0xffff0000, v174
	v_fmac_f32_e32 v188, v115, v119
	v_mul_f32_e32 v115, 0xbfb8aa3b, v116
	v_exp_f32_e32 v115, v115
	v_mul_f32_e32 v116, 0xbfb8aa3b, v117
	v_exp_f32_e32 v116, v116
	v_lshlrev_b32_e32 v118, 16, v174
	v_add_f32_e32 v115, 1.0, v115
	v_rcp_f32_e32 v115, v115
	v_add_f32_e32 v116, 1.0, v116
	v_rcp_f32_e32 v116, v116
	v_fmac_f32_e32 v189, v114, v118
	v_lshlrev_b32_e32 v114, 16, v175
	v_lshlrev_b32_e32 v192, 16, v171
	v_fmac_f32_e32 v192, v115, v114
	v_lshlrev_b64 v[114:115], 12, v[154:155]
	v_and_b32_e32 v117, 0xffff0000, v175
	v_and_b32_e32 v191, 0xffff0000, v171
	v_lshl_add_u64 v[114:115], s[8:9], 0, v[114:115]
	v_fmac_f32_e32 v191, v116, v117
	v_lshl_add_u64 v[116:117], v[114:115], 0, v[122:123]
	v_and_b32_e32 v115, 0xffff0000, v206
	v_lshlrev_b32_e32 v190, 16, v134
	v_and_b32_e32 v134, 0xffff0000, v134
	v_fmac_f32_e32 v134, v111, v115
	v_mul_f32_e32 v111, 0xbfb8aa3b, v112
	v_exp_f32_e32 v111, v111
	v_lshlrev_b32_e32 v114, 16, v206
	v_fmac_f32_e32 v190, v110, v114
	v_lshlrev_b32_e32 v110, 16, v207
	v_add_f32_e32 v111, 1.0, v111
	v_rcp_f32_e32 v111, v111
	v_lshlrev_b32_e32 v193, 16, v135
	v_lshlrev_b32_e32 v194, 16, v136
	v_and_b32_e32 v136, 0xffff0000, v136
	v_fmac_f32_e32 v193, v111, v110
	v_and_b32_e32 v111, 0xffff0000, v208
	v_fmac_f32_e32 v136, v107, v111
	v_mul_f32_e32 v107, 0xbfb8aa3b, v108
	v_mul_f32_e32 v120, 0xbfb8aa3b, v121
	v_exp_f32_e32 v107, v107
	v_exp_f32_e32 v120, v120
	v_mul_f32_e32 v112, 0xbfb8aa3b, v113
	v_exp_f32_e32 v112, v112
	v_mul_f32_e32 v108, 0xbfb8aa3b, v109
	v_add_f32_e32 v106, 1.0, v106
	v_exp_f32_e32 v108, v108
	v_rcp_f32_e32 v106, v106
	v_add_f32_e32 v107, 1.0, v107
	v_exp_f32_e32 v103, v103
	v_add_f32_e32 v120, 1.0, v120
	v_rcp_f32_e32 v107, v107
	v_rcp_f32_e32 v120, v120
	v_add_f32_e32 v112, 1.0, v112
	v_rcp_f32_e32 v112, v112
	v_lshlrev_b32_e32 v110, 16, v208
	v_add_f32_e32 v108, 1.0, v108
	v_fmac_f32_e32 v194, v106, v110
	v_lshlrev_b32_e32 v106, 16, v209
	v_rcp_f32_e32 v108, v108
	v_lshlrev_b32_e32 v195, 16, v137
	v_add_f32_e32 v103, 1.0, v103
	v_and_b32_e32 v121, 0xffff0000, v173
	v_and_b32_e32 v186, 0xffff0000, v169
	v_fmac_f32_e32 v195, v107, v106
	v_lshlrev_b64 v[106:107], 12, v[156:157]
	v_rcp_f32_e32 v103, v103
	v_fmac_f32_e32 v186, v120, v121
	v_cvt_pk_bf16_f32 v118, v184, v185
	v_cvt_pk_bf16_f32 v119, v187, v186
	v_and_b32_e32 v113, 0xffff0000, v207
	v_and_b32_e32 v135, 0xffff0000, v135
	v_lshl_add_u64 v[106:107], s[8:9], 0, v[106:107]
	v_cvt_pk_bf16_f32 v120, v189, v188
	v_cvt_pk_bf16_f32 v121, v192, v191
	global_store_dwordx4 v[116:117], v[118:121], off
	v_fmac_f32_e32 v135, v112, v113
	v_and_b32_e32 v109, 0xffff0000, v209
	v_and_b32_e32 v137, 0xffff0000, v137
	v_lshl_add_u64 v[118:119], v[106:107], 0, v[122:123]
	v_cvt_pk_bf16_f32 v106, v190, v134
	v_cvt_pk_bf16_f32 v107, v193, v135
	v_fmac_f32_e32 v137, v108, v109
	v_cvt_pk_bf16_f32 v108, v194, v136
	v_cvt_pk_bf16_f32 v109, v195, v137
	global_store_dwordx4 v[118:119], v[106:109], off
	v_mul_f32_e32 v102, 0xbfb8aa3b, v102
	v_exp_f32_e32 v102, v102
	v_lshlrev_b32_e32 v106, 16, v130
	v_and_b32_e32 v107, 0xffff0000, v130
	v_lshlrev_b32_e32 v130, 16, v126
	v_and_b32_e32 v126, 0xffff0000, v126
	v_fmac_f32_e32 v126, v103, v107
	v_mul_f32_e32 v103, 0xbfb8aa3b, v104
	v_exp_f32_e32 v103, v103
	v_mul_f32_e32 v99, 0xbfb8aa3b, v99
	v_exp_f32_e32 v99, v99
	v_add_f32_e32 v102, 1.0, v102
	v_rcp_f32_e32 v102, v102
	v_add_f32_e32 v103, 1.0, v103
	v_rcp_f32_e32 v103, v103
	v_add_f32_e32 v99, 1.0, v99
	v_rcp_f32_e32 v99, v99
	v_fmac_f32_e32 v130, v102, v106
	v_lshlrev_b32_e32 v102, 16, v131
	v_mul_f32_e32 v104, 0xbfb8aa3b, v105
	v_and_b32_e32 v105, 0xffff0000, v131
	v_lshlrev_b32_e32 v131, 16, v127
	v_fmac_f32_e32 v131, v103, v102
; __device__ __forceinline__ float sigmoid_f(float x) { return __builtin_amdgcn_rcpf(1.0f + __builtin_amdgcn_exp2f(-x * 1.4426950408889634f)); }
;     __device__ __forceinline__ void operator()(const f32x4 (&acc)[2][2][4][2], const Unit& u, int wr, int wc, int fr, int fq) const {
;     ...
;             for (int bj = 0; bj < 2; ++bj) { const int col = u.pn * BM + bj * HALF + wc * 32 + fq * 8;
;                 u32x4 hw[4], pw[4];
; #pragma unroll
;                 for (int m = 0; m < 4; ++m) { const size_t off = (size_t)(row0 + ai * HALF + m * 16) * DM + col; hw[m] = *(const u32x4*)(HBi + off); pw[m] = *(const u32x4*)(P + off); }
;                 asm volatile("" ::: "memory");
; #pragma unroll
;                 for (int m = 0; m < 4; ++m) { const size_t off = (size_t)(row0 + ai * HALF + m * 16) * DM + col; float v[8];
; #pragma unroll
;                     for (int e = 0; e < 4; ++e) {
;                         const unsigned w = pw[m][e]; const float p0 = __uint_as_float(w << 16), p1 = __uint_as_float(w & 0xffff0000u);
;                         const unsigned g = hw[m][e]; const float b0 = __uint_as_float(g << 16), b1 = __uint_as_float(g & 0xffff0000u);
;                         const float a0 = (e < 2) ? acc[ai][bj][m][0][2 * e] : acc[ai][bj][m][1][2 * e - 4], a1 = (e < 2) ? acc[ai][bj][m][0][2 * e + 1] : acc[ai][bj][m][1][2 * e - 3];
;                         v[2 * e] = b0 + p0 * sigmoid_f(a0); v[2 * e + 1] = b1 + p1 * sigmoid_f(a1); }
; #pragma unroll
;                     for (int e = 0; e < 8; ++e) s[m] += v[e] * v[e];
;                     store8(HBo + off, v); }
	v_lshlrev_b32_e32 v102, 16, v132
	v_mul_f32_e32 v98, 0xbfb8aa3b, v98
	v_and_b32_e32 v103, 0xffff0000, v132
	v_lshlrev_b32_e32 v132, 16, v128
	v_and_b32_e32 v128, 0xffff0000, v128
	v_exp_f32_e32 v98, v98
	v_fmac_f32_e32 v128, v99, v103
	v_mul_f32_e32 v99, 0xbfb8aa3b, v100
	v_exp_f32_e32 v99, v99
	v_exp_f32_e32 v104, v104
	v_mul_f32_e32 v100, 0xbfb8aa3b, v101
	v_add_f32_e32 v98, 1.0, v98
	v_exp_f32_e32 v100, v100
	v_rcp_f32_e32 v98, v98
	v_add_f32_e32 v99, 1.0, v99
	v_rcp_f32_e32 v99, v99
	v_add_f32_e32 v104, 1.0, v104
	v_rcp_f32_e32 v104, v104
	v_add_f32_e32 v100, 1.0, v100
	v_fmac_f32_e32 v132, v98, v102
	v_lshlrev_b32_e32 v98, 16, v133
	v_and_b32_e32 v101, 0xffff0000, v133
	v_rcp_f32_e32 v100, v100
	v_lshlrev_b32_e32 v133, 16, v129
	v_fmac_f32_e32 v133, v99, v98
	v_lshlrev_b64 v[98:99], 12, v[152:153]
	v_and_b32_e32 v127, 0xffff0000, v127
	v_lshl_add_u64 v[98:99], s[8:9], 0, v[98:99]
	v_or_b32_e32 v114, 0x80, v148
	v_fmac_f32_e32 v127, v104, v105
	v_and_b32_e32 v129, 0xffff0000, v129
	v_lshl_add_u64 v[120:121], v[98:99], 0, v[122:123]
	v_cvt_pk_bf16_f32 v98, v130, v126
	v_cvt_pk_bf16_f32 v99, v131, v127
	v_ashrrev_i32_e32 v115, 31, v114
	v_fmac_f32_e32 v129, v100, v101
	v_cvt_pk_bf16_f32 v100, v132, v128
	v_cvt_pk_bf16_f32 v101, v133, v129
	global_store_dwordx4 v[120:121], v[98:101], off
	v_mul_f32_e32 v174, v198, v198
	v_fmac_f32_e32 v174, v197, v197
	v_lshl_add_u64 v[98:99], v[158:159], 0, v[114:115]
	v_lshlrev_b64 v[98:99], 1, v[98:99]
	v_lshl_add_u64 v[100:101], s[10:11], 0, v[98:99]
	v_lshl_add_u64 v[98:99], s[0:1], 0, v[98:99]
	v_mov_b32_e32 v158, v216
	v_mov_b32_e32 v159, v217
	v_mov_b32_e32 v160, v218
	v_mov_b32_e32 v161, v219
	v_mov_b32_e32 v162, v220
	v_mov_b32_e32 v163, v221
	v_mov_b32_e32 v164, v222
	v_mov_b32_e32 v165, v223
	v_fmac_f32_e32 v174, v199, v199
	v_fmac_f32_e32 v174, v200, v200
	v_fmac_f32_e32 v174, v201, v201
	v_lshl_add_u64 v[98:99], v[176:177], 0, v[114:115]
	v_fmac_f32_e32 v174, v166, v166
	v_lshlrev_b64 v[98:99], 1, v[98:99]
	v_fmac_f32_e32 v174, v210, v210
	v_lshl_add_u64 v[100:101], s[0:1], 0, v[98:99]
	v_fmac_f32_e32 v174, v167, v167
	v_lshl_add_u64 v[98:99], s[10:11], 0, v[98:99]
	v_mov_b32_e32 v166, v224
	v_mov_b32_e32 v167, v225
	v_mov_b32_e32 v168, v226
	v_mov_b32_e32 v169, v227
	v_mov_b32_e32 v170, v228
	v_mov_b32_e32 v171, v229
	v_mov_b32_e32 v172, v230
	v_mov_b32_e32 v173, v231
	v_lshl_add_u64 v[98:99], v[180:181], 0, v[114:115]
	v_lshlrev_b64 v[98:99], 1, v[98:99]
	v_lshl_add_u64 v[100:101], s[0:1], 0, v[98:99]
	v_lshl_add_u64 v[98:99], s[10:11], 0, v[98:99]
	v_mov_b32_e32 v106, v232
	v_mov_b32_e32 v107, v233
	v_mov_b32_e32 v108, v234
	v_mov_b32_e32 v109, v235
	v_mov_b32_e32 v110, v236
	v_mov_b32_e32 v111, v237
	v_mov_b32_e32 v112, v238
	v_mov_b32_e32 v113, v239
	v_lshl_add_u64 v[98:99], v[178:179], 0, v[114:115]
	v_lshlrev_b64 v[98:99], 1, v[98:99]
	v_lshl_add_u64 v[100:101], s[0:1], 0, v[98:99]
	v_lshl_add_u64 v[102:103], s[10:11], 0, v[98:99]
	v_mov_b32_e32 v98, v240
	v_mov_b32_e32 v99, v241
	v_mov_b32_e32 v100, v242
	v_mov_b32_e32 v101, v243
	s_nop 0
	v_mov_b32_e32 v102, v244
	v_mov_b32_e32 v103, v245
	v_mov_b32_e32 v104, v246
	v_mov_b32_e32 v105, v247
	v_mul_f32_e32 v95, 0xbfb8aa3b, v95
	v_exp_f32_e32 v95, v95
	v_mul_f32_e32 v94, 0xbfb8aa3b, v94
	v_exp_f32_e32 v94, v94
	v_mul_f32_e32 v91, 0xbfb8aa3b, v91
	v_add_f32_e32 v95, 1.0, v95
	v_rcp_f32_e32 v95, v95
	v_exp_f32_e32 v91, v91
	v_add_f32_e32 v94, 1.0, v94
	v_rcp_f32_e32 v94, v94
	v_mul_f32_e32 v90, 0xbfb8aa3b, v90
	v_add_f32_e32 v91, 1.0, v91
	v_rcp_f32_e32 v91, v91
	v_exp_f32_e32 v90, v90
	v_mul_f32_e32 v86, 0xbfb8aa3b, v86
	v_exp_f32_e32 v86, v86
	v_mul_f32_e32 v87, 0xbfb8aa3b, v87
	v_add_f32_e32 v90, 1.0, v90
	v_rcp_f32_e32 v90, v90
	v_exp_f32_e32 v87, v87
	v_mul_f32_e32 v88, 0xbfb8aa3b, v88
	v_add_f32_e32 v86, 1.0, v86
	v_exp_f32_e32 v88, v88
	v_mul_f32_e32 v89, 0xbfb8aa3b, v89
	v_exp_f32_e32 v89, v89
	v_mul_f32_e32 v82, 0xbfb8aa3b, v82
	v_add_f32_e32 v88, 1.0, v88
	v_exp_f32_e32 v82, v82
	v_mul_f32_e32 v83, 0xbfb8aa3b, v83
	v_exp_f32_e32 v83, v83
	v_mul_f32_e32 v84, 0xbfb8aa3b, v84
	v_exp_f32_e32 v84, v84
	v_mul_f32_e32 v85, 0xbfb8aa3b, v85
	v_exp_f32_e32 v85, v85
	v_add_f32_e32 v82, 1.0, v82
	v_add_f32_e32 v84, 1.0, v84
	v_mul_f32_e32 v78, 0xbfb8aa3b, v78
	v_rcp_f32_e32 v84, v84
	v_add_f32_e32 v85, 1.0, v85
	v_exp_f32_e32 v78, v78
	v_mul_f32_e32 v79, 0xbfb8aa3b, v79
	v_rcp_f32_e32 v85, v85
	v_exp_f32_e32 v79, v79
	v_mul_f32_e32 v80, 0xbfb8aa3b, v80
	v_add_f32_e32 v78, 1.0, v78
	v_exp_f32_e32 v80, v80
	v_mul_f32_e32 v81, 0xbfb8aa3b, v81
	v_exp_f32_e32 v81, v81
	v_mul_f32_e32 v74, 0xbfb8aa3b, v74
	v_add_f32_e32 v80, 1.0, v80
	v_exp_f32_e32 v74, v74
	v_mul_f32_e32 v75, 0xbfb8aa3b, v75
	v_exp_f32_e32 v75, v75
	v_mul_f32_e32 v76, 0xbfb8aa3b, v76
	v_add_f32_e32 v74, 1.0, v74
	v_exp_f32_e32 v76, v76
	s_waitcnt vmcnt(7)
	v_lshlrev_b32_e32 v175, 16, v158
	v_and_b32_e32 v158, 0xffff0000, v158
	s_waitcnt vmcnt(6)
; __device__ __forceinline__ float sigmoid_f(float x) { return __builtin_amdgcn_rcpf(1.0f + __builtin_amdgcn_exp2f(-x * 1.4426950408889634f)); }
;     __device__ __forceinline__ void operator()(const f32x4 (&acc)[2][2][4][2], const Unit& u, int wr, int wc, int fr, int fq) const {
;     ...
;                 for (int m = 0; m < 4; ++m) { const size_t off = (size_t)(row0 + ai * HALF + m * 16) * DM + col; float v[8];
; #pragma unroll
;                     for (int e = 0; e < 4; ++e) {
;                         const unsigned w = pw[m][e]; const float p0 = __uint_as_float(w << 16), p1 = __uint_as_float(w & 0xffff0000u);
;                         const unsigned g = hw[m][e]; const float b0 = __uint_as_float(g << 16), b1 = __uint_as_float(g & 0xffff0000u);
;                         const float a0 = (e < 2) ? acc[ai][bj][m][0][2 * e] : acc[ai][bj][m][1][2 * e - 4], a1 = (e < 2) ? acc[ai][bj][m][0][2 * e + 1] : acc[ai][bj][m][1][2 * e - 3];
;                         v[2 * e] = b0 + p0 * sigmoid_f(a0); v[2 * e + 1] = b1 + p1 * sigmoid_f(a1); }
; #pragma unroll
;                     for (int e = 0; e < 8; ++e) s[m] += v[e] * v[e];
;                     store8(HBo + off, v); }
;                 asm volatile("" ::: "memory"); }
; #pragma unroll
;             for (int m = 0; m < 4; ++m) { float t = s[m]; t += __shfl_xor(t, 16); t += __shfl_xor(t, 32);
;                 if (fq == 0) ssq[(size_t)(row0 + ai * HALF + m * 16) * 32 + u.pn * 4 + wc] = t; }
	v_lshlrev_b32_e32 v176, 16, v162
	v_and_b32_e32 v162, 0xffff0000, v162
	v_fmac_f32_e32 v162, v95, v158
	v_mul_f32_e32 v95, 0xbfb8aa3b, v96
	v_mul_f32_e32 v96, 0xbfb8aa3b, v97
	v_exp_f32_e32 v95, v95
	v_exp_f32_e32 v96, v96
	v_fmac_f32_e32 v176, v94, v175
	v_lshlrev_b32_e32 v94, 16, v159
	v_add_f32_e32 v95, 1.0, v95
	v_add_f32_e32 v96, 1.0, v96
	v_rcp_f32_e32 v95, v95
	v_rcp_f32_e32 v96, v96
	v_and_b32_e32 v97, 0xffff0000, v159
	v_lshlrev_b32_e32 v158, 16, v163
	v_and_b32_e32 v159, 0xffff0000, v163
	v_fmac_f32_e32 v158, v95, v94
	v_fmac_f32_e32 v159, v96, v97
	v_and_b32_e32 v95, 0xffff0000, v160
	v_and_b32_e32 v97, 0xffff0000, v164
	v_fmac_f32_e32 v97, v91, v95
	v_mul_f32_e32 v91, 0xbfb8aa3b, v92
	v_mul_f32_e32 v92, 0xbfb8aa3b, v93
	v_exp_f32_e32 v91, v91
	v_exp_f32_e32 v92, v92
	v_lshlrev_b32_e32 v94, 16, v160
	v_lshlrev_b32_e32 v96, 16, v164
	v_add_f32_e32 v91, 1.0, v91
	v_add_f32_e32 v92, 1.0, v92
	v_rcp_f32_e32 v91, v91
	v_rcp_f32_e32 v92, v92
	v_fmac_f32_e32 v96, v90, v94
	v_lshlrev_b32_e32 v90, 16, v161
	v_and_b32_e32 v93, 0xffff0000, v161
	v_lshlrev_b32_e32 v94, 16, v165
	v_and_b32_e32 v95, 0xffff0000, v165
	v_fmac_f32_e32 v94, v91, v90
	v_fmac_f32_e32 v95, v92, v93
	v_cvt_pk_bf16_f32 v90, v176, v162
	v_cvt_pk_bf16_f32 v91, v158, v159
	v_cvt_pk_bf16_f32 v92, v96, v97
	v_cvt_pk_bf16_f32 v93, v94, v95
	global_store_dwordx4 v[124:125], v[90:93], off offset:256
	v_fmac_f32_e32 v174, v176, v176
	v_fmac_f32_e32 v174, v162, v162
	v_rcp_f32_e32 v92, v86
	v_add_f32_e32 v86, 1.0, v87
	v_rcp_f32_e32 v93, v86
	s_waitcnt vmcnt(5)
	v_lshlrev_b32_e32 v90, 16, v170
	v_lshlrev_b32_e32 v87, 16, v166
	v_and_b32_e32 v91, 0xffff0000, v170
	v_and_b32_e32 v86, 0xffff0000, v166
	v_fmac_f32_e32 v87, v92, v90
	v_rcp_f32_e32 v92, v88
	v_add_f32_e32 v88, 1.0, v89
	v_fmac_f32_e32 v86, v93, v91
	v_rcp_f32_e32 v93, v88
	v_lshlrev_b32_e32 v90, 16, v171
	v_lshlrev_b32_e32 v89, 16, v167
	v_and_b32_e32 v91, 0xffff0000, v171
	v_and_b32_e32 v88, 0xffff0000, v167
	v_fmac_f32_e32 v89, v92, v90
	v_rcp_f32_e32 v92, v82
	v_add_f32_e32 v82, 1.0, v83
	v_fmac_f32_e32 v88, v93, v91
	v_rcp_f32_e32 v93, v82
	v_fmac_f32_e32 v174, v158, v158
	v_fmac_f32_e32 v174, v159, v159
	v_fmac_f32_e32 v174, v96, v96
	v_lshlrev_b32_e32 v90, 16, v172
	v_and_b32_e32 v91, 0xffff0000, v172
	v_lshlrev_b32_e32 v83, 16, v168
	v_and_b32_e32 v82, 0xffff0000, v168
	v_fmac_f32_e32 v174, v97, v97
	v_fmac_f32_e32 v83, v92, v90
	v_fmac_f32_e32 v82, v93, v91
	v_lshlrev_b32_e32 v92, 16, v173
	v_lshlrev_b32_e32 v91, 16, v169
	v_fmac_f32_e32 v174, v94, v94
	v_and_b32_e32 v93, 0xffff0000, v173
	v_and_b32_e32 v90, 0xffff0000, v169
	v_fmac_f32_e32 v91, v84, v92
	v_cvt_pk_bf16_f32 v92, v87, v86
	v_fmac_f32_e32 v174, v95, v95
	v_fmac_f32_e32 v90, v85, v93
	v_cvt_pk_bf16_f32 v93, v89, v88
	v_cvt_pk_bf16_f32 v94, v83, v82
	v_cvt_pk_bf16_f32 v95, v91, v90
	global_store_dwordx4 v[116:117], v[92:95], off offset:256
	s_waitcnt vmcnt(4)
	v_lshlrev_b32_e32 v84, 16, v110
	v_and_b32_e32 v85, 0xffff0000, v110
	v_rcp_f32_e32 v92, v78
	v_add_f32_e32 v78, 1.0, v79
	v_rcp_f32_e32 v93, v78
	v_lshlrev_b32_e32 v79, 16, v106
	v_and_b32_e32 v78, 0xffff0000, v106
	v_fmac_f32_e32 v79, v92, v84
	v_rcp_f32_e32 v92, v80
	v_add_f32_e32 v80, 1.0, v81
	v_fmac_f32_e32 v78, v93, v85
	v_rcp_f32_e32 v93, v80
	v_lshlrev_b32_e32 v84, 16, v111
	v_lshlrev_b32_e32 v81, 16, v107
	v_mul_f32_e32 v77, 0xbfb8aa3b, v77
	v_and_b32_e32 v85, 0xffff0000, v111
	v_and_b32_e32 v80, 0xffff0000, v107
	v_fmac_f32_e32 v81, v92, v84
	v_rcp_f32_e32 v92, v74
	v_add_f32_e32 v74, 1.0, v75
	v_exp_f32_e32 v77, v77
	v_fmac_f32_e32 v80, v93, v85
	v_rcp_f32_e32 v93, v74
	v_lshlrev_b32_e32 v84, 16, v112
	v_lshlrev_b32_e32 v75, 16, v108
	v_add_f32_e32 v76, 1.0, v76
	v_mul_f32_e32 v70, 0xbfb8aa3b, v70
	v_and_b32_e32 v85, 0xffff0000, v112
	v_and_b32_e32 v74, 0xffff0000, v108
	v_fmac_f32_e32 v75, v92, v84
	v_rcp_f32_e32 v92, v76
	v_add_f32_e32 v76, 1.0, v77
	v_exp_f32_e32 v70, v70
	v_mul_f32_e32 v71, 0xbfb8aa3b, v71
	v_fmac_f32_e32 v74, v93, v85
	v_rcp_f32_e32 v93, v76
	v_exp_f32_e32 v71, v71
	v_lshlrev_b32_e32 v84, 16, v113
	v_lshlrev_b32_e32 v77, 16, v109
	v_mul_f32_e32 v72, 0xbfb8aa3b, v72
	v_and_b32_e32 v85, 0xffff0000, v113
	v_and_b32_e32 v76, 0xffff0000, v109
	v_fmac_f32_e32 v77, v92, v84
	v_cvt_pk_bf16_f32 v92, v79, v78
	v_add_f32_e32 v70, 1.0, v70
	v_exp_f32_e32 v72, v72
	v_mul_f32_e32 v73, 0xbfb8aa3b, v73
	v_fmac_f32_e32 v76, v93, v85
	v_cvt_pk_bf16_f32 v93, v81, v80
	v_cvt_pk_bf16_f32 v94, v75, v74
	v_cvt_pk_bf16_f32 v95, v77, v76
	global_store_dwordx4 v[118:119], v[92:95], off offset:256
	v_exp_f32_e32 v73, v73
	v_mul_f32_e32 v66, 0xbfb8aa3b, v66
	v_rcp_f32_e32 v92, v70
	v_add_f32_e32 v70, 1.0, v71
	v_rcp_f32_e32 v93, v70
	s_waitcnt vmcnt(3)
	v_lshlrev_b32_e32 v84, 16, v102
	v_lshlrev_b32_e32 v71, 16, v98
	v_add_f32_e32 v72, 1.0, v72
	v_exp_f32_e32 v66, v66
	v_mul_f32_e32 v67, 0xbfb8aa3b, v67
	v_and_b32_e32 v85, 0xffff0000, v102
	v_and_b32_e32 v70, 0xffff0000, v98
	v_fmac_f32_e32 v71, v92, v84
	v_rcp_f32_e32 v92, v72
	v_add_f32_e32 v72, 1.0, v73
	v_exp_f32_e32 v67, v67
	v_fmac_f32_e32 v70, v93, v85
	v_rcp_f32_e32 v93, v72
	v_mul_f32_e32 v68, 0xbfb8aa3b, v68
	v_lshlrev_b32_e32 v84, 16, v103
	v_lshlrev_b32_e32 v73, 16, v99
	v_add_f32_e32 v66, 1.0, v66
	v_exp_f32_e32 v68, v68
	v_mul_f32_e32 v69, 0xbfb8aa3b, v69
	v_and_b32_e32 v85, 0xffff0000, v103
	v_and_b32_e32 v72, 0xffff0000, v99
	v_fmac_f32_e32 v73, v92, v84
	v_rcp_f32_e32 v92, v66
	v_add_f32_e32 v66, 1.0, v67
	v_exp_f32_e32 v69, v69
	v_fmac_f32_e32 v72, v93, v85
	v_rcp_f32_e32 v93, v66
	v_lshlrev_b32_e32 v84, 16, v104
	v_lshlrev_b32_e32 v67, 16, v100
	v_add_f32_e32 v68, 1.0, v68
	v_and_b32_e32 v85, 0xffff0000, v104
	v_and_b32_e32 v66, 0xffff0000, v100
	v_fmac_f32_e32 v67, v92, v84
	v_rcp_f32_e32 v92, v68
	v_add_f32_e32 v68, 1.0, v69
	v_fmac_f32_e32 v66, v93, v85
	v_rcp_f32_e32 v93, v68
	v_and_b32_e32 v85, 0xffff0000, v105
	v_and_b32_e32 v68, 0xffff0000, v101
	v_lshlrev_b32_e32 v84, 16, v105
	v_lshlrev_b32_e32 v69, 16, v101
	v_fmac_f32_e32 v68, v93, v85
	v_and_b32_e32 v85, 64, v202
	v_fmac_f32_e32 v69, v92, v84
	v_xor_b32_e32 v84, 16, v202
	v_add_u32_e32 v85, 64, v85
	v_cvt_pk_bf16_f32 v92, v71, v70
	v_cmp_lt_i32_e64 s[4:5], v84, v85
	v_cvt_pk_bf16_f32 v93, v73, v72
	v_cvt_pk_bf16_f32 v94, v67, v66
	v_cvt_pk_bf16_f32 v95, v69, v68
	global_store_dwordx4 v[120:121], v[92:95], off offset:256
	s_nop 0
	v_cndmask_b32_e64 v84, v202, v84, s[4:5]
	v_lshlrev_b32_e32 v84, 2, v84
	v_xor_b32_e32 v92, 32, v202
	v_cmp_lt_i32_e64 s[4:5], v92, v85
	v_cmp_eq_u32_e32 vcc, 0, v196
	s_nop 0
	v_cndmask_b32_e64 v85, v202, v92, s[4:5]
	ds_bpermute_b32 v92, v84, v174
	s_lshl_b32 s4, s51, 2
	v_lshlrev_b32_e32 v85, 2, v85
	s_ashr_i32 s5, s4, 31
	s_lshl_b64 s[4:5], s[4:5], 2
	s_waitcnt lgkmcnt(0)
	v_add_f32_e32 v92, v174, v92
	ds_bpermute_b32 v93, v85, v92
	s_add_u32 s4, s46, s4
	s_addc_u32 s5, s47, s5
	s_lshl_b32 s15, s15, 2
	s_add_u32 s4, s4, s15
	s_addc_u32 s5, s5, 0
	s_and_saveexec_b64 s[24:25], vcc
	s_cbranch_execz .LBB0_1347
;     __device__ __forceinline__ void operator()(const f32x4 (&acc)[2][2][4][2], const Unit& u, int wr, int wc, int fr, int fq) const {
;     ...
;             for (int m = 0; m < 4; ++m) { float t = s[m]; t += __shfl_xor(t, 16); t += __shfl_xor(t, 32);
;                 if (fq == 0) ssq[(size_t)(row0 + ai * HALF + m * 16) * 32 + u.pn * 4 + wc] = t; }
	v_lshlrev_b64 v[94:95], 7, v[150:151]
	v_lshl_add_u64 v[94:95], s[4:5], 0, v[94:95]
	s_waitcnt lgkmcnt(0)
	v_add_f32_e32 v92, v92, v93
	global_store_dword v[94:95], v92, off

; __device__ __forceinline__ float sigmoid_f(float x) { return __builtin_amdgcn_rcpf(1.0f + __builtin_amdgcn_exp2f(-x * 1.4426950408889634f)); }
;     __device__ __forceinline__ void operator()(const f32x4 (&acc)[2][2][4][2], const Unit& u, int wr, int wc, int fr, int fq) const {
;     ...
;         for (int ai = 0; ai < 2; ++ai) {
;             float s[4] = {0.f, 0.f, 0.f, 0.f};
; #pragma unroll
;             for (int bj = 0; bj < 2; ++bj) { const int col = u.pn * BM + bj * HALF + wc * 32 + fq * 8;
;                 u32x4 hw[4], pw[4];
; #pragma unroll
;                 for (int m = 0; m < 4; ++m) { const size_t off = (size_t)(row0 + ai * HALF + m * 16) * DM + col; hw[m] = *(const u32x4*)(HBi + off); pw[m] = *(const u32x4*)(P + off); }
;                 asm volatile("" ::: "memory");
; #pragma unroll
;                 for (int m = 0; m < 4; ++m) { const size_t off = (size_t)(row0 + ai * HALF + m * 16) * DM + col; float v[8];
; #pragma unroll
;                     for (int e = 0; e < 4; ++e) {
;                         const unsigned w = pw[m][e]; const float p0 = __uint_as_float(w << 16), p1 = __uint_as_float(w & 0xffff0000u);
;                         const unsigned g = hw[m][e]; const float b0 = __uint_as_float(g << 16), b1 = __uint_as_float(g & 0xffff0000u);
;                         const float a0 = (e < 2) ? acc[ai][bj][m][0][2 * e] : acc[ai][bj][m][1][2 * e - 4], a1 = (e < 2) ? acc[ai][bj][m][0][2 * e + 1] : acc[ai][bj][m][1][2 * e - 3];
;                         v[2 * e] = b0 + p0 * sigmoid_f(a0); v[2 * e + 1] = b1 + p1 * sigmoid_f(a1); }
.LBB0_1353:
	s_or_b64 exec, exec, s[24:25]
	v_add_u32_e32 v72, 0x80, v150
	v_ashrrev_i32_e32 v73, 31, v72
	v_lshlrev_b64 v[74:75], 11, v[72:73]
	s_waitcnt lgkmcnt(0)
	v_lshl_add_u64 v[66:67], v[74:75], 0, v[148:149]
	v_lshlrev_b64 v[66:67], 1, v[66:67]
	v_lshl_add_u64 v[68:69], s[10:11], 0, v[66:67]
	v_lshl_add_u64 v[66:67], s[0:1], 0, v[66:67]
	global_load_dwordx4 v[216:219], v[68:69], off offset:256
	global_load_dwordx4 v[86:89], v[68:69], off
	global_load_dwordx4 v[220:223], v[66:67], off offset:256
	global_load_dwordx4 v[90:93], v[66:67], off
	v_add_u32_e32 v70, 0x90, v150
	v_ashrrev_i32_e32 v71, 31, v70
	v_lshlrev_b64 v[76:77], 11, v[70:71]
	v_mul_f32_e32 v80, 0xbfb8aa3b, v62
	v_mul_f32_e32 v81, 0xbfb8aa3b, v63
	v_lshl_add_u64 v[62:63], v[76:77], 0, v[148:149]
	v_lshlrev_b64 v[62:63], 1, v[62:63]
	v_lshl_add_u64 v[78:79], s[0:1], 0, v[62:63]
	v_lshl_add_u64 v[62:63], s[10:11], 0, v[62:63]
	global_load_dwordx4 v[224:227], v[78:79], off offset:256
	global_load_dwordx4 v[94:97], v[78:79], off
	global_load_dwordx4 v[228:231], v[62:63], off offset:256
	global_load_dwordx4 v[98:101], v[62:63], off
	v_add_u32_e32 v68, 0xa0, v150
	v_add_u32_e32 v66, 0xb0, v150
	v_mul_f32_e32 v62, 0xbfb8aa3b, v64
	v_mul_f32_e32 v63, 0xbfb8aa3b, v65
	v_mul_f32_e32 v58, 0xbfb8aa3b, v58
	v_mul_f32_e32 v59, 0xbfb8aa3b, v59
	v_mul_f32_e32 v60, 0xbfb8aa3b, v60
	v_mul_f32_e32 v61, 0xbfb8aa3b, v61
	v_ashrrev_i32_e32 v69, 31, v68
	v_ashrrev_i32_e32 v67, 31, v66
	v_exp_f32_e32 v102, v80
	v_exp_f32_e32 v103, v81
	v_exp_f32_e32 v104, v62
	v_exp_f32_e32 v105, v63
	v_exp_f32_e32 v106, v58
	v_exp_f32_e32 v107, v59
	v_exp_f32_e32 v108, v60
	v_exp_f32_e32 v109, v61
	v_lshlrev_b64 v[82:83], 11, v[68:69]
	v_lshlrev_b64 v[80:81], 11, v[66:67]
	v_lshl_add_u64 v[58:59], v[82:83], 0, v[148:149]
	v_lshl_add_u64 v[60:61], v[80:81], 0, v[148:149]
	v_lshlrev_b64 v[58:59], 1, v[58:59]
	v_lshlrev_b64 v[60:61], 1, v[60:61]
	v_lshl_add_u64 v[62:63], s[0:1], 0, v[58:59]
	v_lshl_add_u64 v[58:59], s[10:11], 0, v[58:59]
	v_lshl_add_u64 v[64:65], s[0:1], 0, v[60:61]
	v_lshl_add_u64 v[78:79], s[10:11], 0, v[60:61]
	v_add_f32_e32 v110, 1.0, v102
	v_add_f32_e32 v111, 1.0, v103
	v_add_f32_e32 v112, 1.0, v104
	v_add_f32_e32 v113, 1.0, v105
	v_add_f32_e32 v116, 1.0, v106
	v_add_f32_e32 v117, 1.0, v107
	v_add_f32_e32 v118, 1.0, v108
	v_add_f32_e32 v119, 1.0, v109
	global_load_dwordx4 v[232:235], v[62:63], off offset:256
	global_load_dwordx4 v[102:105], v[62:63], off
	global_load_dwordx4 v[236:239], v[58:59], off offset:256
	global_load_dwordx4 v[106:109], v[58:59], off
	s_nop 0
	global_load_dwordx4 v[240:243], v[64:65], off offset:256
	global_load_dwordx4 v[58:61], v[64:65], off
	s_nop 0
	global_load_dwordx4 v[244:247], v[78:79], off offset:256
	global_load_dwordx4 v[62:65], v[78:79], off
	v_rcp_f32_e32 v78, v110
	v_mul_f32_e32 v55, 0xbfb8aa3b, v55
	v_rcp_f32_e32 v79, v111
	v_rcp_f32_e32 v110, v112
	v_rcp_f32_e32 v111, v113
	v_rcp_f32_e32 v112, v116
	v_rcp_f32_e32 v113, v117
	v_rcp_f32_e32 v116, v118
	v_exp_f32_e32 v55, v55
	v_mul_f32_e32 v54, 0xbfb8aa3b, v54
	v_exp_f32_e32 v54, v54
	v_add_f32_e32 v55, 1.0, v55
	v_rcp_f32_e32 v55, v55
	v_mul_f32_e32 v51, 0xbfb8aa3b, v51
	v_exp_f32_e32 v51, v51
	v_add_f32_e32 v54, 1.0, v54
	v_rcp_f32_e32 v54, v54
	v_mul_f32_e32 v50, 0xbfb8aa3b, v50
	v_add_f32_e32 v51, 1.0, v51
	v_rcp_f32_e32 v51, v51
	v_exp_f32_e32 v50, v50
	v_mul_f32_e32 v47, 0xbfb8aa3b, v47
	v_exp_f32_e32 v47, v47
	v_mul_f32_e32 v46, 0xbfb8aa3b, v46
	v_add_f32_e32 v50, 1.0, v50
	v_rcp_f32_e32 v50, v50
	v_add_f32_e32 v47, 1.0, v47
	v_rcp_f32_e32 v47, v47
	v_exp_f32_e32 v46, v46
	v_mul_f32_e32 v43, 0xbfb8aa3b, v43
	s_waitcnt vmcnt(7)
	v_lshlrev_b32_e32 v117, 16, v86
	s_waitcnt vmcnt(6)
	v_lshlrev_b32_e32 v118, 16, v90
	v_fmac_f32_e32 v118, v78, v117
	v_rcp_f32_e32 v78, v119
	v_and_b32_e32 v120, 0xffff0000, v90
	v_lshlrev_b32_e32 v90, 16, v87
	v_and_b32_e32 v87, 0xffff0000, v87
	v_and_b32_e32 v124, 0xffff0000, v91
	v_and_b32_e32 v86, 0xffff0000, v86
	v_lshlrev_b32_e32 v125, 16, v92
	v_and_b32_e32 v126, 0xffff0000, v92
	v_lshlrev_b32_e32 v92, 16, v89
	v_and_b32_e32 v89, 0xffff0000, v89
	v_fmac_f32_e32 v124, v111, v87
	v_and_b32_e32 v111, 0xffff0000, v93
	v_lshlrev_b32_e32 v121, 16, v91
	v_fmac_f32_e32 v120, v79, v86
	v_fmac_f32_e32 v111, v78, v89
	v_lshlrev_b64 v[78:79], 12, v[72:73]
	v_lshlrev_b32_e32 v91, 16, v88
	v_and_b32_e32 v88, 0xffff0000, v88
	v_fmac_f32_e32 v121, v110, v90
	v_lshlrev_b32_e32 v110, 16, v93
	v_lshl_add_u64 v[78:79], s[8:9], 0, v[78:79]
	v_fmac_f32_e32 v125, v112, v91
	v_fmac_f32_e32 v126, v113, v88
	v_fmac_f32_e32 v110, v116, v92
	v_lshl_add_u64 v[78:79], v[78:79], 0, v[122:123]
	v_cvt_pk_bf16_f32 v86, v118, v120
	v_cvt_pk_bf16_f32 v87, v121, v124
	v_cvt_pk_bf16_f32 v88, v125, v126
	v_cvt_pk_bf16_f32 v89, v110, v111
	global_store_dwordx4 v[78:79], v[86:89], off
	s_waitcnt vmcnt(6)
	v_lshlrev_b32_e32 v92, 16, v97
	v_and_b32_e32 v91, 0xffff0000, v97
	s_waitcnt vmcnt(5)
; __device__ __forceinline__ float sigmoid_f(float x) { return __builtin_amdgcn_rcpf(1.0f + __builtin_amdgcn_exp2f(-x * 1.4426950408889634f)); }
;     __device__ __forceinline__ void operator()(const f32x4 (&acc)[2][2][4][2], const Unit& u, int wr, int wc, int fr, int fq) const {
;     ...
;                 for (int m = 0; m < 4; ++m) { const size_t off = (size_t)(row0 + ai * HALF + m * 16) * DM + col; float v[8];
; #pragma unroll
;                     for (int e = 0; e < 4; ++e) {
;                         const unsigned w = pw[m][e]; const float p0 = __uint_as_float(w << 16), p1 = __uint_as_float(w & 0xffff0000u);
;                         const unsigned g = hw[m][e]; const float b0 = __uint_as_float(g << 16), b1 = __uint_as_float(g & 0xffff0000u);
;                         const float a0 = (e < 2) ? acc[ai][bj][m][0][2 * e] : acc[ai][bj][m][1][2 * e - 4], a1 = (e < 2) ? acc[ai][bj][m][0][2 * e + 1] : acc[ai][bj][m][1][2 * e - 3];
;                         v[2 * e] = b0 + p0 * sigmoid_f(a0); v[2 * e + 1] = b1 + p1 * sigmoid_f(a1); }
; #pragma unroll
;                     for (int e = 0; e < 8; ++e) s[m] += v[e] * v[e];
;                     store8(HBo + off, v); }
	v_and_b32_e32 v89, 0xffff0000, v98
	v_and_b32_e32 v87, 0xffff0000, v94
	v_fmac_f32_e32 v87, v55, v89
	v_mul_f32_e32 v55, 0xbfb8aa3b, v56
	v_mul_f32_e32 v56, 0xbfb8aa3b, v57
	v_exp_f32_e32 v55, v55
	v_exp_f32_e32 v56, v56
	v_lshlrev_b32_e32 v88, 16, v98
	v_lshlrev_b32_e32 v86, 16, v94
	v_add_f32_e32 v55, 1.0, v55
	v_add_f32_e32 v56, 1.0, v56
	v_rcp_f32_e32 v55, v55
	v_rcp_f32_e32 v89, v56
	v_fmac_f32_e32 v86, v54, v88
	v_lshlrev_b32_e32 v54, 16, v99
	v_and_b32_e32 v88, 0xffff0000, v99
	v_lshlrev_b32_e32 v57, 16, v95
	v_and_b32_e32 v56, 0xffff0000, v95
	v_fmac_f32_e32 v57, v55, v54
	v_fmac_f32_e32 v56, v89, v88
	v_and_b32_e32 v55, 0xffff0000, v100
	v_and_b32_e32 v88, 0xffff0000, v96
	v_fmac_f32_e32 v88, v51, v55
	v_mul_f32_e32 v51, 0xbfb8aa3b, v52
	v_exp_f32_e32 v51, v51
	v_mul_f32_e32 v52, 0xbfb8aa3b, v53
	v_exp_f32_e32 v52, v52
	v_lshlrev_b32_e32 v54, 16, v100
	v_add_f32_e32 v51, 1.0, v51
	v_rcp_f32_e32 v51, v51
	v_add_f32_e32 v52, 1.0, v52
	v_lshlrev_b32_e32 v89, 16, v96
	v_rcp_f32_e32 v52, v52
	v_fmac_f32_e32 v89, v50, v54
	v_lshlrev_b32_e32 v50, 16, v101
	v_fmac_f32_e32 v92, v51, v50
	v_lshlrev_b64 v[50:51], 12, v[70:71]
	v_and_b32_e32 v53, 0xffff0000, v101
	v_lshl_add_u64 v[50:51], s[8:9], 0, v[50:51]
	v_fmac_f32_e32 v91, v52, v53
	v_lshl_add_u64 v[50:51], v[50:51], 0, v[122:123]
	v_cvt_pk_bf16_f32 v52, v86, v87
	v_cvt_pk_bf16_f32 v53, v57, v56
	v_cvt_pk_bf16_f32 v54, v89, v88
	v_cvt_pk_bf16_f32 v55, v92, v91
	global_store_dwordx4 v[50:51], v[52:55], off
	s_waitcnt vmcnt(5)
	v_and_b32_e32 v93, 0xffff0000, v102
	v_exp_f32_e32 v43, v43
	s_waitcnt vmcnt(4)
	v_and_b32_e32 v53, 0xffff0000, v106
	v_fmac_f32_e32 v93, v47, v53
	v_mul_f32_e32 v47, 0xbfb8aa3b, v48
	v_exp_f32_e32 v47, v47
	v_add_f32_e32 v46, 1.0, v46
	v_rcp_f32_e32 v46, v46
	v_add_f32_e32 v43, 1.0, v43
	v_add_f32_e32 v47, 1.0, v47
	v_rcp_f32_e32 v47, v47
	v_rcp_f32_e32 v43, v43
	v_lshlrev_b32_e32 v52, 16, v106
	v_lshlrev_b32_e32 v90, 16, v102
	v_fmac_f32_e32 v90, v46, v52
	v_lshlrev_b32_e32 v46, 16, v107
	v_lshlrev_b32_e32 v95, 16, v103
	v_fmac_f32_e32 v95, v47, v46
	v_mul_f32_e32 v42, 0xbfb8aa3b, v42
	v_and_b32_e32 v47, 0xffff0000, v108
	v_and_b32_e32 v96, 0xffff0000, v104
	v_exp_f32_e32 v42, v42
	v_fmac_f32_e32 v96, v43, v47
	v_mul_f32_e32 v43, 0xbfb8aa3b, v44
	v_exp_f32_e32 v43, v43
	v_mul_f32_e32 v48, 0xbfb8aa3b, v49
	v_exp_f32_e32 v48, v48
	v_mul_f32_e32 v44, 0xbfb8aa3b, v45
	v_add_f32_e32 v42, 1.0, v42
	v_exp_f32_e32 v44, v44
	v_mul_f32_e32 v39, 0xbfb8aa3b, v39
	v_rcp_f32_e32 v42, v42
	v_add_f32_e32 v43, 1.0, v43
	v_exp_f32_e32 v39, v39
	v_rcp_f32_e32 v43, v43
	v_add_f32_e32 v48, 1.0, v48
	v_rcp_f32_e32 v48, v48
	v_lshlrev_b32_e32 v46, 16, v108
	v_lshlrev_b32_e32 v97, 16, v104
	v_add_f32_e32 v44, 1.0, v44
	v_fmac_f32_e32 v97, v42, v46
	v_lshlrev_b32_e32 v42, 16, v109
	v_rcp_f32_e32 v44, v44
	v_lshlrev_b32_e32 v99, 16, v105
	v_add_f32_e32 v39, 1.0, v39
	v_fmac_f32_e32 v99, v43, v42
	v_lshlrev_b64 v[42:43], 12, v[68:69]
	v_rcp_f32_e32 v39, v39
	v_and_b32_e32 v49, 0xffff0000, v107
	v_and_b32_e32 v94, 0xffff0000, v103
	v_lshl_add_u64 v[42:43], s[8:9], 0, v[42:43]
	v_fmac_f32_e32 v94, v48, v49
	v_and_b32_e32 v45, 0xffff0000, v109
	v_and_b32_e32 v98, 0xffff0000, v105
	v_lshl_add_u64 v[54:55], v[42:43], 0, v[122:123]
	v_cvt_pk_bf16_f32 v42, v90, v93
	v_cvt_pk_bf16_f32 v43, v95, v94
	v_fmac_f32_e32 v98, v44, v45
	v_cvt_pk_bf16_f32 v44, v97, v96
	v_cvt_pk_bf16_f32 v45, v99, v98
	global_store_dwordx4 v[54:55], v[42:45], off
	v_mul_f32_e32 v38, 0xbfb8aa3b, v38
	v_exp_f32_e32 v38, v38
	s_waitcnt vmcnt(3)
	v_lshlrev_b32_e32 v42, 16, v62
	v_and_b32_e32 v43, 0xffff0000, v62
	v_lshlrev_b32_e32 v62, 16, v58
	v_and_b32_e32 v58, 0xffff0000, v58
	v_fmac_f32_e32 v58, v39, v43
	v_mul_f32_e32 v39, 0xbfb8aa3b, v40
	v_exp_f32_e32 v39, v39
	v_mul_f32_e32 v35, 0xbfb8aa3b, v35
	v_exp_f32_e32 v35, v35
	v_add_f32_e32 v38, 1.0, v38
	v_rcp_f32_e32 v38, v38
	v_add_f32_e32 v39, 1.0, v39
	v_rcp_f32_e32 v39, v39
	v_add_f32_e32 v35, 1.0, v35
	v_rcp_f32_e32 v35, v35
	v_fmac_f32_e32 v62, v38, v42
	v_lshlrev_b32_e32 v38, 16, v63
	v_mul_f32_e32 v40, 0xbfb8aa3b, v41
	v_and_b32_e32 v41, 0xffff0000, v63
	v_lshlrev_b32_e32 v63, 16, v59
	v_fmac_f32_e32 v63, v39, v38
	v_lshlrev_b32_e32 v38, 16, v64
	v_mul_f32_e32 v34, 0xbfb8aa3b, v34
	v_and_b32_e32 v39, 0xffff0000, v64
	v_lshlrev_b32_e32 v64, 16, v60
	v_and_b32_e32 v60, 0xffff0000, v60
	v_exp_f32_e32 v34, v34
	v_fmac_f32_e32 v60, v35, v39
	v_mul_f32_e32 v35, 0xbfb8aa3b, v36
	v_exp_f32_e32 v35, v35
	v_exp_f32_e32 v40, v40
	v_mul_f32_e32 v36, 0xbfb8aa3b, v37
	v_add_f32_e32 v34, 1.0, v34
	v_exp_f32_e32 v36, v36
	v_rcp_f32_e32 v34, v34
	v_add_f32_e32 v35, 1.0, v35
	v_rcp_f32_e32 v35, v35
	v_add_f32_e32 v40, 1.0, v40
	v_rcp_f32_e32 v40, v40
	v_add_f32_e32 v36, 1.0, v36
	v_fmac_f32_e32 v64, v34, v38
	v_lshlrev_b32_e32 v34, 16, v65
	v_and_b32_e32 v37, 0xffff0000, v65
	v_rcp_f32_e32 v36, v36
	v_lshlrev_b32_e32 v65, 16, v61
	v_fmac_f32_e32 v65, v35, v34
	v_lshlrev_b64 v[34:35], 12, v[66:67]
	v_and_b32_e32 v59, 0xffff0000, v59
	v_lshl_add_u64 v[34:35], s[8:9], 0, v[34:35]
	v_fmac_f32_e32 v59, v40, v41
	v_and_b32_e32 v61, 0xffff0000, v61
	v_lshl_add_u64 v[52:53], v[34:35], 0, v[122:123]
	v_cvt_pk_bf16_f32 v34, v62, v58
	v_cvt_pk_bf16_f32 v35, v63, v59
	v_fmac_f32_e32 v61, v36, v37
	v_cvt_pk_bf16_f32 v36, v64, v60
	v_cvt_pk_bf16_f32 v37, v65, v61
	global_store_dwordx4 v[52:53], v[34:37], off
	v_mul_f32_e32 v112, v120, v120
	v_fmac_f32_e32 v112, v118, v118
	v_lshl_add_u64 v[34:35], v[74:75], 0, v[114:115]
	v_lshlrev_b64 v[34:35], 1, v[34:35]
	v_lshl_add_u64 v[36:37], s[10:11], 0, v[34:35]
	v_lshl_add_u64 v[34:35], s[0:1], 0, v[34:35]
	v_mov_b32_e32 v100, v216
	v_mov_b32_e32 v101, v217
; __device__ __forceinline__ float sigmoid_f(float x) { return __builtin_amdgcn_rcpf(1.0f + __builtin_amdgcn_exp2f(-x * 1.4426950408889634f)); }
;     __device__ __forceinline__ void operator()(const f32x4 (&acc)[2][2][4][2], const Unit& u, int wr, int wc, int fr, int fq) const {
;     ...
;             for (int bj = 0; bj < 2; ++bj) { const int col = u.pn * BM + bj * HALF + wc * 32 + fq * 8;
;                 u32x4 hw[4], pw[4];
; #pragma unroll
;                 for (int m = 0; m < 4; ++m) { const size_t off = (size_t)(row0 + ai * HALF + m * 16) * DM + col; hw[m] = *(const u32x4*)(HBi + off); pw[m] = *(const u32x4*)(P + off); }
;                 asm volatile("" ::: "memory");
; #pragma unroll
;                 for (int m = 0; m < 4; ++m) { const size_t off = (size_t)(row0 + ai * HALF + m * 16) * DM + col; float v[8];
; #pragma unroll
;                     for (int e = 0; e < 4; ++e) {
;                         const unsigned w = pw[m][e]; const float p0 = __uint_as_float(w << 16), p1 = __uint_as_float(w & 0xffff0000u);
;                         const unsigned g = hw[m][e]; const float b0 = __uint_as_float(g << 16), b1 = __uint_as_float(g & 0xffff0000u);
;                         const float a0 = (e < 2) ? acc[ai][bj][m][0][2 * e] : acc[ai][bj][m][1][2 * e - 4], a1 = (e < 2) ? acc[ai][bj][m][0][2 * e + 1] : acc[ai][bj][m][1][2 * e - 3];
;                         v[2 * e] = b0 + p0 * sigmoid_f(a0); v[2 * e + 1] = b1 + p1 * sigmoid_f(a1); }
; #pragma unroll
;                     for (int e = 0; e < 8; ++e) s[m] += v[e] * v[e];
;                     store8(HBo + off, v); }
	v_mov_b32_e32 v102, v218
	v_mov_b32_e32 v103, v219
	v_mov_b32_e32 v104, v220
	v_mov_b32_e32 v105, v221
	v_mov_b32_e32 v106, v222
	v_mov_b32_e32 v107, v223
	v_fmac_f32_e32 v112, v121, v121
	v_fmac_f32_e32 v112, v124, v124
	v_fmac_f32_e32 v112, v125, v125
	v_lshl_add_u64 v[34:35], v[76:77], 0, v[114:115]
	v_fmac_f32_e32 v112, v126, v126
	v_lshlrev_b64 v[34:35], 1, v[34:35]
	v_fmac_f32_e32 v112, v110, v110
	v_lshl_add_u64 v[36:37], s[0:1], 0, v[34:35]
	v_fmac_f32_e32 v112, v111, v111
	v_lshl_add_u64 v[34:35], s[10:11], 0, v[34:35]
	v_mov_b32_e32 v74, v224
	v_mov_b32_e32 v75, v225
	v_mov_b32_e32 v76, v226
	v_mov_b32_e32 v77, v227
	v_mov_b32_e32 v108, v228
	v_mov_b32_e32 v109, v229
	v_mov_b32_e32 v110, v230
	v_mov_b32_e32 v111, v231
	v_lshl_add_u64 v[34:35], v[82:83], 0, v[114:115]
	v_lshlrev_b64 v[34:35], 1, v[34:35]
	v_lshl_add_u64 v[36:37], s[0:1], 0, v[34:35]
	v_lshl_add_u64 v[34:35], s[10:11], 0, v[34:35]
	v_mov_b32_e32 v42, v232
	v_mov_b32_e32 v43, v233
	v_mov_b32_e32 v44, v234
	v_mov_b32_e32 v45, v235
	v_mov_b32_e32 v46, v236
	v_mov_b32_e32 v47, v237
	v_mov_b32_e32 v48, v238
	v_mov_b32_e32 v49, v239
	v_lshl_add_u64 v[34:35], v[80:81], 0, v[114:115]
	v_lshlrev_b64 v[34:35], 1, v[34:35]
	v_lshl_add_u64 v[36:37], s[0:1], 0, v[34:35]
	v_lshl_add_u64 v[38:39], s[10:11], 0, v[34:35]
	v_mov_b32_e32 v34, v240
	v_mov_b32_e32 v35, v241
	v_mov_b32_e32 v36, v242
	v_mov_b32_e32 v37, v243
	s_nop 0
	v_mov_b32_e32 v38, v244
	v_mov_b32_e32 v39, v245
	v_mov_b32_e32 v40, v246
	v_mov_b32_e32 v41, v247
	v_mul_f32_e32 v31, 0xbfb8aa3b, v31
	v_exp_f32_e32 v31, v31
	v_mul_f32_e32 v30, 0xbfb8aa3b, v30
	v_exp_f32_e32 v30, v30
	v_mul_f32_e32 v27, 0xbfb8aa3b, v27
	v_add_f32_e32 v31, 1.0, v31
	v_rcp_f32_e32 v31, v31
	v_exp_f32_e32 v27, v27
	v_add_f32_e32 v30, 1.0, v30
	v_rcp_f32_e32 v30, v30
	v_mul_f32_e32 v26, 0xbfb8aa3b, v26
	v_add_f32_e32 v27, 1.0, v27
	v_rcp_f32_e32 v27, v27
	v_exp_f32_e32 v26, v26
	v_mul_f32_e32 v22, 0xbfb8aa3b, v22
	v_exp_f32_e32 v22, v22
	v_mul_f32_e32 v23, 0xbfb8aa3b, v23
	v_add_f32_e32 v26, 1.0, v26
	v_rcp_f32_e32 v26, v26
	v_exp_f32_e32 v23, v23
	v_mul_f32_e32 v24, 0xbfb8aa3b, v24
	v_add_f32_e32 v22, 1.0, v22
	v_exp_f32_e32 v24, v24
	v_mul_f32_e32 v25, 0xbfb8aa3b, v25
	v_exp_f32_e32 v25, v25
	v_mul_f32_e32 v18, 0xbfb8aa3b, v18
	v_add_f32_e32 v24, 1.0, v24
	v_exp_f32_e32 v18, v18
	v_mul_f32_e32 v19, 0xbfb8aa3b, v19
	v_exp_f32_e32 v19, v19
	v_mul_f32_e32 v20, 0xbfb8aa3b, v20
	v_add_f32_e32 v18, 1.0, v18
	v_exp_f32_e32 v20, v20
	v_mul_f32_e32 v21, 0xbfb8aa3b, v21
	v_exp_f32_e32 v21, v21
	v_mul_f32_e32 v14, 0xbfb8aa3b, v14
	v_add_f32_e32 v20, 1.0, v20
	v_exp_f32_e32 v14, v14
	v_mul_f32_e32 v15, 0xbfb8aa3b, v15
	v_exp_f32_e32 v15, v15
	v_mul_f32_e32 v16, 0xbfb8aa3b, v16
	v_add_f32_e32 v14, 1.0, v14
	v_exp_f32_e32 v16, v16
	v_mul_f32_e32 v17, 0xbfb8aa3b, v17
	v_exp_f32_e32 v17, v17
	v_mul_f32_e32 v10, 0xbfb8aa3b, v10
	v_add_f32_e32 v16, 1.0, v16
	v_exp_f32_e32 v10, v10
	v_mul_f32_e32 v11, 0xbfb8aa3b, v11
	v_exp_f32_e32 v11, v11
	v_mul_f32_e32 v12, 0xbfb8aa3b, v12
	v_add_f32_e32 v10, 1.0, v10
	v_exp_f32_e32 v12, v12
	v_mul_f32_e32 v13, 0xbfb8aa3b, v13
	v_exp_f32_e32 v13, v13
	v_mul_f32_e32 v6, 0xbfb8aa3b, v6
	s_waitcnt vmcnt(7)
	v_and_b32_e32 v81, 0xffff0000, v100
	s_waitcnt vmcnt(6)
	v_and_b32_e32 v83, 0xffff0000, v104
	v_fmac_f32_e32 v83, v31, v81
	v_mul_f32_e32 v31, 0xbfb8aa3b, v32
	v_mul_f32_e32 v32, 0xbfb8aa3b, v33
	v_exp_f32_e32 v31, v31
	v_exp_f32_e32 v32, v32
	v_lshlrev_b32_e32 v80, 16, v100
	v_lshlrev_b32_e32 v82, 16, v104
	v_add_f32_e32 v31, 1.0, v31
	v_add_f32_e32 v32, 1.0, v32
	v_rcp_f32_e32 v31, v31
	v_rcp_f32_e32 v32, v32
	v_fmac_f32_e32 v82, v30, v80
	v_lshlrev_b32_e32 v30, 16, v101
	v_and_b32_e32 v33, 0xffff0000, v101
	v_lshlrev_b32_e32 v80, 16, v105
	v_and_b32_e32 v81, 0xffff0000, v105
	v_fmac_f32_e32 v80, v31, v30
	v_fmac_f32_e32 v81, v32, v33
	v_and_b32_e32 v31, 0xffff0000, v102
	v_and_b32_e32 v33, 0xffff0000, v106
	v_fmac_f32_e32 v33, v27, v31
	v_mul_f32_e32 v27, 0xbfb8aa3b, v28
	v_mul_f32_e32 v28, 0xbfb8aa3b, v29
	v_exp_f32_e32 v27, v27
	v_exp_f32_e32 v28, v28
	v_lshlrev_b32_e32 v30, 16, v102
	v_lshlrev_b32_e32 v32, 16, v106
	v_add_f32_e32 v27, 1.0, v27
	v_add_f32_e32 v28, 1.0, v28
	v_rcp_f32_e32 v27, v27
	v_rcp_f32_e32 v28, v28
	v_fmac_f32_e32 v32, v26, v30
	v_lshlrev_b32_e32 v26, 16, v103
	v_and_b32_e32 v29, 0xffff0000, v103
	v_lshlrev_b32_e32 v30, 16, v107
	v_and_b32_e32 v31, 0xffff0000, v107
	v_fmac_f32_e32 v30, v27, v26
	v_fmac_f32_e32 v31, v28, v29
	v_cvt_pk_bf16_f32 v26, v82, v83
	v_cvt_pk_bf16_f32 v27, v80, v81
	v_cvt_pk_bf16_f32 v28, v32, v33
	v_cvt_pk_bf16_f32 v29, v30, v31
	global_store_dwordx4 v[78:79], v[26:29], off offset:256
	v_add_f32_e32 v12, 1.0, v12
	v_exp_f32_e32 v6, v6
	v_rcp_f32_e32 v28, v22
	v_add_f32_e32 v22, 1.0, v23
	v_rcp_f32_e32 v29, v22
	s_waitcnt vmcnt(5)
; __device__ __forceinline__ float sigmoid_f(float x) { return __builtin_amdgcn_rcpf(1.0f + __builtin_amdgcn_exp2f(-x * 1.4426950408889634f)); }
;     __device__ __forceinline__ void operator()(const f32x4 (&acc)[2][2][4][2], const Unit& u, int wr, int wc, int fr, int fq) const {
;     ...
;                 for (int m = 0; m < 4; ++m) { const size_t off = (size_t)(row0 + ai * HALF + m * 16) * DM + col; float v[8];
; #pragma unroll
;                     for (int e = 0; e < 4; ++e) {
;                         const unsigned w = pw[m][e]; const float p0 = __uint_as_float(w << 16), p1 = __uint_as_float(w & 0xffff0000u);
;                         const unsigned g = hw[m][e]; const float b0 = __uint_as_float(g << 16), b1 = __uint_as_float(g & 0xffff0000u);
;                         const float a0 = (e < 2) ? acc[ai][bj][m][0][2 * e] : acc[ai][bj][m][1][2 * e - 4], a1 = (e < 2) ? acc[ai][bj][m][0][2 * e + 1] : acc[ai][bj][m][1][2 * e - 3];
;                         v[2 * e] = b0 + p0 * sigmoid_f(a0); v[2 * e + 1] = b1 + p1 * sigmoid_f(a1); }
; #pragma unroll
;                     for (int e = 0; e < 8; ++e) s[m] += v[e] * v[e];
;                     store8(HBo + off, v); }
;                 asm volatile("" ::: "memory"); }
; #pragma unroll
;             for (int m = 0; m < 4; ++m) { float t = s[m]; t += __shfl_xor(t, 16); t += __shfl_xor(t, 32);
;                 if (fq == 0) ssq[(size_t)(row0 + ai * HALF + m * 16) * 32 + u.pn * 4 + wc] = t; }
	v_lshlrev_b32_e32 v26, 16, v108
	v_lshlrev_b32_e32 v23, 16, v74
	v_and_b32_e32 v27, 0xffff0000, v108
	v_and_b32_e32 v22, 0xffff0000, v74
	v_fmac_f32_e32 v23, v28, v26
	v_rcp_f32_e32 v28, v24
	v_add_f32_e32 v24, 1.0, v25
	v_fmac_f32_e32 v22, v29, v27
	v_rcp_f32_e32 v29, v24
	v_lshlrev_b32_e32 v26, 16, v109
	v_lshlrev_b32_e32 v25, 16, v75
	v_and_b32_e32 v27, 0xffff0000, v109
	v_and_b32_e32 v24, 0xffff0000, v75
	v_fmac_f32_e32 v25, v28, v26
	v_rcp_f32_e32 v28, v18
	v_add_f32_e32 v18, 1.0, v19
	v_fmac_f32_e32 v24, v29, v27
	v_rcp_f32_e32 v29, v18
	v_lshlrev_b32_e32 v26, 16, v110
	v_lshlrev_b32_e32 v19, 16, v76
	v_and_b32_e32 v27, 0xffff0000, v110
	v_and_b32_e32 v18, 0xffff0000, v76
	v_fmac_f32_e32 v19, v28, v26
	v_rcp_f32_e32 v28, v20
	v_add_f32_e32 v20, 1.0, v21
	v_fmac_f32_e32 v18, v29, v27
	v_rcp_f32_e32 v29, v20
	v_lshlrev_b32_e32 v26, 16, v111
	v_and_b32_e32 v27, 0xffff0000, v111
	v_lshlrev_b32_e32 v21, 16, v77
	v_and_b32_e32 v20, 0xffff0000, v77
	v_fmac_f32_e32 v21, v28, v26
	v_fmac_f32_e32 v20, v29, v27
	v_cvt_pk_bf16_f32 v26, v23, v22
	v_cvt_pk_bf16_f32 v27, v25, v24
	v_cvt_pk_bf16_f32 v28, v19, v18
	v_cvt_pk_bf16_f32 v29, v21, v20
	global_store_dwordx4 v[50:51], v[26:29], off offset:256
	v_mul_f32_e32 v7, 0xbfb8aa3b, v7
	v_exp_f32_e32 v7, v7
	v_rcp_f32_e32 v28, v14
	v_add_f32_e32 v14, 1.0, v15
	v_rcp_f32_e32 v29, v14
	s_waitcnt vmcnt(4)
	v_lshlrev_b32_e32 v26, 16, v46
	v_lshlrev_b32_e32 v15, 16, v42
	v_and_b32_e32 v27, 0xffff0000, v46
	v_and_b32_e32 v14, 0xffff0000, v42
	v_fmac_f32_e32 v15, v28, v26
	v_rcp_f32_e32 v28, v16
	v_add_f32_e32 v16, 1.0, v17
	v_fmac_f32_e32 v14, v29, v27
	v_rcp_f32_e32 v29, v16
	v_lshlrev_b32_e32 v26, 16, v47
	v_lshlrev_b32_e32 v17, 16, v43
	v_and_b32_e32 v27, 0xffff0000, v47
	v_and_b32_e32 v16, 0xffff0000, v43
	v_fmac_f32_e32 v17, v28, v26
	v_rcp_f32_e32 v28, v10
	v_add_f32_e32 v10, 1.0, v11
	v_fmac_f32_e32 v16, v29, v27
	v_rcp_f32_e32 v29, v10
	v_lshlrev_b32_e32 v26, 16, v48
	v_lshlrev_b32_e32 v11, 16, v44
	v_and_b32_e32 v27, 0xffff0000, v48
	v_and_b32_e32 v10, 0xffff0000, v44
	v_fmac_f32_e32 v11, v28, v26
	v_rcp_f32_e32 v28, v12
	v_add_f32_e32 v12, 1.0, v13
	v_fmac_f32_e32 v10, v29, v27
	v_rcp_f32_e32 v29, v12
	v_lshlrev_b32_e32 v26, 16, v49
	v_and_b32_e32 v27, 0xffff0000, v49
	v_lshlrev_b32_e32 v13, 16, v45
	v_and_b32_e32 v12, 0xffff0000, v45
	v_mul_f32_e32 v8, 0xbfb8aa3b, v8
	v_fmac_f32_e32 v13, v28, v26
	v_fmac_f32_e32 v12, v29, v27
	v_cvt_pk_bf16_f32 v26, v15, v14
	v_cvt_pk_bf16_f32 v27, v17, v16
	v_cvt_pk_bf16_f32 v28, v11, v10
	v_add_f32_e32 v6, 1.0, v6
	v_exp_f32_e32 v8, v8
	v_mul_f32_e32 v9, 0xbfb8aa3b, v9
	v_cvt_pk_bf16_f32 v29, v13, v12
	global_store_dwordx4 v[54:55], v[26:29], off offset:256
	v_exp_f32_e32 v9, v9
	v_mul_f32_e32 v2, 0xbfb8aa3b, v2
	v_rcp_f32_e32 v28, v6
	v_add_f32_e32 v6, 1.0, v7
	v_rcp_f32_e32 v29, v6
	s_waitcnt vmcnt(3)
	v_lshlrev_b32_e32 v26, 16, v38
	v_lshlrev_b32_e32 v7, 16, v34
	v_add_f32_e32 v8, 1.0, v8
	v_exp_f32_e32 v2, v2
	v_mul_f32_e32 v3, 0xbfb8aa3b, v3
	v_fmac_f32_e32 v112, v82, v82
	v_and_b32_e32 v27, 0xffff0000, v38
	v_and_b32_e32 v6, 0xffff0000, v34
	v_fmac_f32_e32 v7, v28, v26
	v_rcp_f32_e32 v28, v8
	v_add_f32_e32 v8, 1.0, v9
	v_exp_f32_e32 v3, v3
	v_fmac_f32_e32 v112, v83, v83
	v_fmac_f32_e32 v6, v29, v27
	v_rcp_f32_e32 v29, v8
	v_fmac_f32_e32 v112, v80, v80
	v_mul_f32_e32 v4, 0xbfb8aa3b, v4
	v_fmac_f32_e32 v112, v81, v81
	v_lshlrev_b32_e32 v26, 16, v39
	v_lshlrev_b32_e32 v9, 16, v35
	v_add_f32_e32 v2, 1.0, v2
	v_exp_f32_e32 v4, v4
	v_mul_f32_e32 v5, 0xbfb8aa3b, v5
	v_fmac_f32_e32 v112, v32, v32
	v_and_b32_e32 v27, 0xffff0000, v39
	v_and_b32_e32 v8, 0xffff0000, v35
	v_fmac_f32_e32 v9, v28, v26
	v_rcp_f32_e32 v28, v2
	v_add_f32_e32 v2, 1.0, v3
	v_exp_f32_e32 v5, v5
	v_fmac_f32_e32 v112, v33, v33
	v_fmac_f32_e32 v8, v29, v27
	v_rcp_f32_e32 v29, v2
	v_fmac_f32_e32 v112, v30, v30
	v_fmac_f32_e32 v112, v31, v31
	v_lshlrev_b32_e32 v26, 16, v40
	v_lshlrev_b32_e32 v3, 16, v36
	v_add_f32_e32 v4, 1.0, v4
	v_and_b32_e32 v27, 0xffff0000, v40
	v_and_b32_e32 v2, 0xffff0000, v36
	v_fmac_f32_e32 v3, v28, v26
	v_rcp_f32_e32 v28, v4
	v_add_f32_e32 v4, 1.0, v5
	ds_bpermute_b32 v30, v84, v112
	v_fmac_f32_e32 v2, v29, v27
	v_rcp_f32_e32 v29, v4
	v_lshlrev_b32_e32 v26, 16, v41
	v_lshlrev_b32_e32 v5, 16, v37
	v_and_b32_e32 v27, 0xffff0000, v41
	v_and_b32_e32 v4, 0xffff0000, v37
	v_fmac_f32_e32 v5, v28, v26
	v_cvt_pk_bf16_f32 v26, v7, v6
	v_fmac_f32_e32 v4, v29, v27
	v_cvt_pk_bf16_f32 v27, v9, v8
	v_cvt_pk_bf16_f32 v28, v3, v2
	v_cvt_pk_bf16_f32 v29, v5, v4
	global_store_dwordx4 v[52:53], v[26:29], off offset:256
	s_waitcnt lgkmcnt(0)
	s_nop 0
	v_add_f32_e32 v26, v112, v30
	ds_bpermute_b32 v27, v85, v26
	s_and_saveexec_b64 s[24:25], vcc
	s_cbranch_execz .LBB0_1355
	v_lshlrev_b64 v[28:29], 7, v[72:73]
	v_lshl_add_u64 v[28:29], s[4:5], 0, v[28:29]
	s_waitcnt lgkmcnt(0)
	v_add_f32_e32 v26, v26, v27
	global_store_dword v[28:29], v26, off
